# P1 K-loop: removed compiler-inserted loop-head s_waitcnt vmcnt(0) (counted vmcnt(8) waits + barriers already order LDS-DMA before ds_read, as in the P4 instance)
# speedup vs baseline: 1.0039x; 1.0016x over previous
.LBB0_165:
	ds_read_b128 v[114:117], v177
	ds_read_b128 v[118:121], v177 offset:1024
	ds_read_b128 v[122:125], v177 offset:2048
	ds_read_b128 v[126:129], v177 offset:3072
	ds_read_b128 v[182:185], v178
	ds_read_b128 v[186:189], v178 offset:1024
	ds_read_b128 v[190:193], v178 offset:2048
	ds_read_b128 v[194:197], v178 offset:3072
	s_add_u32 s0, s70, 0xfff80080
	s_addc_u32 s1, s71, -1
	s_cmp_eq_u32 s76, 28
	s_cselect_b32 s13, s9, s1
	s_cselect_b32 s12, s61, s0
	s_cselect_b32 s1, s63, s21
	s_cselect_b32 s0, s75, s20
	v_lshl_add_u64 v[174:175], s[70:71], 0, v[166:167]
	s_add_i32 m0, s35, 0xc000
	ds_read_b128 v[198:201], v179
	ds_read_b128 v[202:205], v179 offset:1024
	ds_read_b128 v[206:209], v179 offset:2048
	ds_read_b128 v[210:213], v179 offset:3072
	ds_read_b128 v[214:217], v179 offset:4096
	ds_read_b128 v[218:221], v179 offset:5120
	ds_read_b128 v[222:225], v179 offset:6144
	ds_read_b128 v[226:229], v179 offset:7168
	global_load_lds_dwordx4 v[174:175], off
	v_lshl_add_u64 v[174:175], s[70:71], 0, v[168:169]
	s_add_i32 m0, s35, 0xe000
	s_nop 0
	global_load_lds_dwordx4 v[174:175], off
	s_waitcnt vmcnt(8)
	s_waitcnt lgkmcnt(0)
	s_barrier
	s_setprio 1
	s_waitcnt lgkmcnt(0)
	v_mfma_f32_16x16x32_bf16 v[142:145], v[114:117], v[198:201], v[142:145]
	v_mfma_f32_16x16x32_bf16 v[138:141], v[122:125], v[198:201], v[138:141]
	v_mfma_f32_16x16x32_bf16 v[110:113], v[114:117], v[206:209], v[110:113]
	v_mfma_f32_16x16x32_bf16 v[106:109], v[122:125], v[206:209], v[106:109]
	v_mfma_f32_16x16x32_bf16 v[94:97], v[114:117], v[214:217], v[94:97]
	v_mfma_f32_16x16x32_bf16 v[90:93], v[122:125], v[214:217], v[90:93]
	v_mfma_f32_16x16x32_bf16 v[78:81], v[114:117], v[222:225], v[78:81]
	v_mfma_f32_16x16x32_bf16 v[74:77], v[122:125], v[222:225], v[74:77]
	v_mfma_f32_16x16x32_bf16 v[142:145], v[118:121], v[202:205], v[142:145]
	v_mfma_f32_16x16x32_bf16 v[138:141], v[126:129], v[202:205], v[138:141]
	v_mfma_f32_16x16x32_bf16 v[110:113], v[118:121], v[210:213], v[110:113]
	v_mfma_f32_16x16x32_bf16 v[106:109], v[126:129], v[210:213], v[106:109]
	v_mfma_f32_16x16x32_bf16 v[94:97], v[118:121], v[218:221], v[94:97]
	v_mfma_f32_16x16x32_bf16 v[90:93], v[126:129], v[218:221], v[90:93]
	v_mfma_f32_16x16x32_bf16 v[78:81], v[118:121], v[226:229], v[78:81]
	v_mfma_f32_16x16x32_bf16 v[74:77], v[126:129], v[226:229], v[74:77]
	s_setprio 0
	s_setprio 1
	v_mfma_f32_16x16x32_bf16 v[134:137], v[182:185], v[198:201], v[134:137]
	v_mfma_f32_16x16x32_bf16 v[130:133], v[190:193], v[198:201], v[130:133]
	v_mfma_f32_16x16x32_bf16 v[102:105], v[182:185], v[206:209], v[102:105]
	v_mfma_f32_16x16x32_bf16 v[98:101], v[190:193], v[206:209], v[98:101]
	v_mfma_f32_16x16x32_bf16 v[86:89], v[182:185], v[214:217], v[86:89]
	v_mfma_f32_16x16x32_bf16 v[82:85], v[190:193], v[214:217], v[82:85]
	v_mfma_f32_16x16x32_bf16 v[70:73], v[182:185], v[222:225], v[70:73]
	v_mfma_f32_16x16x32_bf16 v[66:69], v[190:193], v[222:225], v[66:69]
	v_mfma_f32_16x16x32_bf16 v[134:137], v[186:189], v[202:205], v[134:137]
	v_mfma_f32_16x16x32_bf16 v[130:133], v[194:197], v[202:205], v[130:133]
	v_mfma_f32_16x16x32_bf16 v[102:105], v[186:189], v[210:213], v[102:105]
	v_mfma_f32_16x16x32_bf16 v[98:101], v[194:197], v[210:213], v[98:101]
	v_mfma_f32_16x16x32_bf16 v[86:89], v[186:189], v[218:221], v[86:89]
	v_mfma_f32_16x16x32_bf16 v[82:85], v[194:197], v[218:221], v[82:85]
	v_mfma_f32_16x16x32_bf16 v[70:73], v[186:189], v[226:229], v[70:73]
	v_mfma_f32_16x16x32_bf16 v[66:69], v[194:197], v[226:229], v[66:69]
	s_setprio 0
	s_barrier
	s_add_i32 s77, s72, s34
	v_lshl_add_u64 v[174:175], s[0:1], 0, v[148:149]
	s_mov_b32 m0, s77
	ds_read_b128 v[198:201], v179 offset:16384
	ds_read_b128 v[202:205], v179 offset:17408
	ds_read_b128 v[206:209], v179 offset:18432
	ds_read_b128 v[210:213], v179 offset:19456
	ds_read_b128 v[214:217], v179 offset:20480
	ds_read_b128 v[218:221], v179 offset:21504
	ds_read_b128 v[222:225], v179 offset:22528
	ds_read_b128 v[226:229], v179 offset:23552
	global_load_lds_dwordx4 v[174:175], off
	s_add_i32 m0, s77, 0x2000
	s_add_u32 s78, s0, 0x20000
	v_lshl_add_u64 v[230:231], s[0:1], 0, v[152:153]
	s_addc_u32 s79, s1, 0
	s_add_i32 s77, s73, s34
	global_load_lds_dwordx4 v[230:231], off
	v_lshl_add_u64 v[232:233], s[78:79], 0, v[148:149]
	s_mov_b32 m0, s77
	v_lshl_add_u64 v[234:235], s[12:13], 0, v[150:151]
	global_load_lds_dwordx4 v[232:233], off
	v_lshl_add_u64 v[232:233], s[78:79], 0, v[152:153]
	s_add_i32 m0, s77, 0x2000
	s_nop 0
	global_load_lds_dwordx4 v[232:233], off
	v_lshl_add_u64 v[232:233], s[12:13], 0, v[146:147]
	s_mov_b32 m0, s35
	s_nop 0
	global_load_lds_dwordx4 v[232:233], off
	s_mov_b32 m0, s36
	s_nop 0
	global_load_lds_dwordx4 v[234:235], off
	s_waitcnt vmcnt(8)
	s_waitcnt lgkmcnt(0)
	s_barrier
	s_setprio 1
	s_waitcnt lgkmcnt(0)
	v_mfma_f32_16x16x32_bf16 v[62:65], v[114:117], v[198:201], v[62:65]
	v_mfma_f32_16x16x32_bf16 v[58:61], v[122:125], v[198:201], v[58:61]
	v_mfma_f32_16x16x32_bf16 v[46:49], v[114:117], v[206:209], v[46:49]
	v_mfma_f32_16x16x32_bf16 v[42:45], v[122:125], v[206:209], v[42:45]
	v_mfma_f32_16x16x32_bf16 v[30:33], v[114:117], v[214:217], v[30:33]
	v_mfma_f32_16x16x32_bf16 v[26:29], v[122:125], v[214:217], v[26:29]
	v_mfma_f32_16x16x32_bf16 v[14:17], v[114:117], v[222:225], v[14:17]
	v_mfma_f32_16x16x32_bf16 v[10:13], v[122:125], v[222:225], v[10:13]
	v_mfma_f32_16x16x32_bf16 v[62:65], v[118:121], v[202:205], v[62:65]
	v_mfma_f32_16x16x32_bf16 v[58:61], v[126:129], v[202:205], v[58:61]
	v_mfma_f32_16x16x32_bf16 v[46:49], v[118:121], v[210:213], v[46:49]
	v_mfma_f32_16x16x32_bf16 v[42:45], v[126:129], v[210:213], v[42:45]
	v_mfma_f32_16x16x32_bf16 v[30:33], v[118:121], v[218:221], v[30:33]
	v_mfma_f32_16x16x32_bf16 v[26:29], v[126:129], v[218:221], v[26:29]
	v_mfma_f32_16x16x32_bf16 v[14:17], v[118:121], v[226:229], v[14:17]
	v_mfma_f32_16x16x32_bf16 v[10:13], v[126:129], v[226:229], v[10:13]
	s_setprio 0
	s_setprio 1
	v_mfma_f32_16x16x32_bf16 v[54:57], v[182:185], v[198:201], v[54:57]
	v_mfma_f32_16x16x32_bf16 v[50:53], v[190:193], v[198:201], v[50:53]
	v_mfma_f32_16x16x32_bf16 v[38:41], v[182:185], v[206:209], v[38:41]
	v_mfma_f32_16x16x32_bf16 v[34:37], v[190:193], v[206:209], v[34:37]
	v_mfma_f32_16x16x32_bf16 v[22:25], v[182:185], v[214:217], v[22:25]
	v_mfma_f32_16x16x32_bf16 v[18:21], v[190:193], v[214:217], v[18:21]
	v_mfma_f32_16x16x32_bf16 v[6:9], v[182:185], v[222:225], v[6:9]
	v_mfma_f32_16x16x32_bf16 v[2:5], v[190:193], v[222:225], v[2:5]
	v_mfma_f32_16x16x32_bf16 v[54:57], v[186:189], v[202:205], v[54:57]
	v_mfma_f32_16x16x32_bf16 v[50:53], v[194:197], v[202:205], v[50:53]
	v_mfma_f32_16x16x32_bf16 v[38:41], v[186:189], v[210:213], v[38:41]
	v_mfma_f32_16x16x32_bf16 v[34:37], v[194:197], v[210:213], v[34:37]
	v_mfma_f32_16x16x32_bf16 v[22:25], v[186:189], v[218:221], v[22:25]
	v_mfma_f32_16x16x32_bf16 v[18:21], v[194:197], v[218:221], v[18:21]
	v_mfma_f32_16x16x32_bf16 v[6:9], v[186:189], v[226:229], v[6:9]
	v_mfma_f32_16x16x32_bf16 v[2:5], v[194:197], v[226:229], v[2:5]
	s_setprio 0
	s_barrier
	s_add_i32 s77, 0, 0x18000
	s_add_i32 s78, 0, 0x1c000
	v_add_u32_e32 v126, s77, v159
	v_add_u32_e32 v154, s78, v159
	ds_read_b128 v[114:117], v126
	ds_read_b128 v[118:121], v126 offset:1024
	ds_read_b128 v[122:125], v126 offset:2048
	ds_read_b128 v[126:129], v126 offset:3072
	ds_read_b128 v[182:185], v154
	ds_read_b128 v[186:189], v154 offset:1024
	ds_read_b128 v[190:193], v154 offset:2048
	ds_read_b128 v[194:197], v154 offset:3072
	s_add_u32 s12, s12, 0x80000
	s_addc_u32 s13, s13, 0
	s_mov_b32 m0, s37
	v_lshl_add_u64 v[236:237], s[12:13], 0, v[146:147]
	ds_read_b128 v[198:201], v179 offset:32768
	ds_read_b128 v[202:205], v179 offset:33792
	ds_read_b128 v[206:209], v179 offset:34816
	ds_read_b128 v[210:213], v179 offset:35840
	ds_read_b128 v[214:217], v179 offset:36864
	ds_read_b128 v[218:221], v179 offset:37888
	ds_read_b128 v[222:225], v179 offset:38912
	ds_read_b128 v[226:229], v179 offset:39936
	global_load_lds_dwordx4 v[236:237], off
	v_lshl_add_u64 v[236:237], s[12:13], 0, v[150:151]
	s_mov_b32 m0, s38
	s_nop 0
	global_load_lds_dwordx4 v[236:237], off
	s_waitcnt vmcnt(8)
	s_waitcnt lgkmcnt(0)
	s_barrier
	s_setprio 1
	s_waitcnt lgkmcnt(0)
	v_mfma_f32_16x16x32_bf16 v[142:145], v[114:117], v[198:201], v[142:145]
	v_mfma_f32_16x16x32_bf16 v[138:141], v[122:125], v[198:201], v[138:141]
	v_mfma_f32_16x16x32_bf16 v[110:113], v[114:117], v[206:209], v[110:113]
	v_mfma_f32_16x16x32_bf16 v[106:109], v[122:125], v[206:209], v[106:109]
	v_mfma_f32_16x16x32_bf16 v[94:97], v[114:117], v[214:217], v[94:97]
	v_mfma_f32_16x16x32_bf16 v[90:93], v[122:125], v[214:217], v[90:93]
	v_mfma_f32_16x16x32_bf16 v[78:81], v[114:117], v[222:225], v[78:81]
	v_mfma_f32_16x16x32_bf16 v[74:77], v[122:125], v[222:225], v[74:77]
	v_mfma_f32_16x16x32_bf16 v[142:145], v[118:121], v[202:205], v[142:145]
	v_mfma_f32_16x16x32_bf16 v[138:141], v[126:129], v[202:205], v[138:141]
	v_mfma_f32_16x16x32_bf16 v[110:113], v[118:121], v[210:213], v[110:113]
	v_mfma_f32_16x16x32_bf16 v[106:109], v[126:129], v[210:213], v[106:109]
	v_mfma_f32_16x16x32_bf16 v[94:97], v[118:121], v[218:221], v[94:97]
	v_mfma_f32_16x16x32_bf16 v[90:93], v[126:129], v[218:221], v[90:93]
	v_mfma_f32_16x16x32_bf16 v[78:81], v[118:121], v[226:229], v[78:81]
	v_mfma_f32_16x16x32_bf16 v[74:77], v[126:129], v[226:229], v[74:77]
	s_setprio 0
	s_setprio 1
	v_mfma_f32_16x16x32_bf16 v[134:137], v[182:185], v[198:201], v[134:137]
	v_mfma_f32_16x16x32_bf16 v[130:133], v[190:193], v[198:201], v[130:133]
	v_mfma_f32_16x16x32_bf16 v[102:105], v[182:185], v[206:209], v[102:105]
	v_mfma_f32_16x16x32_bf16 v[98:101], v[190:193], v[206:209], v[98:101]
	v_mfma_f32_16x16x32_bf16 v[86:89], v[182:185], v[214:217], v[86:89]
	v_mfma_f32_16x16x32_bf16 v[82:85], v[190:193], v[214:217], v[82:85]
	v_mfma_f32_16x16x32_bf16 v[70:73], v[182:185], v[222:225], v[70:73]
	v_mfma_f32_16x16x32_bf16 v[66:69], v[190:193], v[222:225], v[66:69]
	v_mfma_f32_16x16x32_bf16 v[134:137], v[186:189], v[202:205], v[134:137]
	v_mfma_f32_16x16x32_bf16 v[130:133], v[194:197], v[202:205], v[130:133]
	v_mfma_f32_16x16x32_bf16 v[102:105], v[186:189], v[210:213], v[102:105]
	v_mfma_f32_16x16x32_bf16 v[98:101], v[194:197], v[210:213], v[98:101]
	v_mfma_f32_16x16x32_bf16 v[86:89], v[186:189], v[218:221], v[86:89]
	v_mfma_f32_16x16x32_bf16 v[82:85], v[194:197], v[218:221], v[82:85]
	v_mfma_f32_16x16x32_bf16 v[70:73], v[186:189], v[226:229], v[70:73]
	v_mfma_f32_16x16x32_bf16 v[66:69], v[194:197], v[226:229], v[66:69]
	s_setprio 0
	s_barrier
	s_add_i32 s12, s77, s34
	v_lshl_add_u64 v[174:175], v[174:175], 0, s[52:53]
	s_mov_b32 m0, s12
	ds_read_b128 v[198:201], v179 offset:49152
	ds_read_b128 v[202:205], v179 offset:50176
	ds_read_b128 v[206:209], v179 offset:51200
	ds_read_b128 v[210:213], v179 offset:52224
	ds_read_b128 v[214:217], v179 offset:53248
	ds_read_b128 v[218:221], v179 offset:54272
	ds_read_b128 v[222:225], v179 offset:55296
	ds_read_b128 v[226:229], v179 offset:56320
	global_load_lds_dwordx4 v[174:175], off
	s_add_i32 m0, s12, 0x2000
	s_add_u32 s0, s0, 0x20080
	v_lshl_add_u64 v[174:175], v[230:231], 0, s[52:53]
	s_addc_u32 s1, s1, 0
	s_add_i32 s12, s78, s34
	global_load_lds_dwordx4 v[174:175], off
	v_lshl_add_u64 v[174:175], s[0:1], 0, v[148:149]
	s_mov_b32 m0, s12
	s_nop 0
	global_load_lds_dwordx4 v[174:175], off
	v_lshl_add_u64 v[174:175], s[0:1], 0, v[152:153]
	s_add_i32 m0, s12, 0x2000
	s_nop 0
	global_load_lds_dwordx4 v[174:175], off
	v_lshl_add_u64 v[174:175], v[232:233], 0, s[52:53]
	s_mov_b32 m0, s44
	s_nop 0
	global_load_lds_dwordx4 v[174:175], off
	v_lshl_add_u64 v[174:175], v[234:235], 0, s[52:53]
	s_mov_b32 m0, s45
	s_nop 0
	global_load_lds_dwordx4 v[174:175], off
	s_waitcnt vmcnt(8)
	s_waitcnt lgkmcnt(0)
	s_barrier
	s_setprio 1
	s_waitcnt lgkmcnt(0)
	v_mfma_f32_16x16x32_bf16 v[62:65], v[114:117], v[198:201], v[62:65]
	v_mfma_f32_16x16x32_bf16 v[58:61], v[122:125], v[198:201], v[58:61]
	v_mfma_f32_16x16x32_bf16 v[46:49], v[114:117], v[206:209], v[46:49]
	v_mfma_f32_16x16x32_bf16 v[42:45], v[122:125], v[206:209], v[42:45]
	v_mfma_f32_16x16x32_bf16 v[30:33], v[114:117], v[214:217], v[30:33]
	v_mfma_f32_16x16x32_bf16 v[26:29], v[122:125], v[214:217], v[26:29]
	v_mfma_f32_16x16x32_bf16 v[14:17], v[114:117], v[222:225], v[14:17]
	v_mfma_f32_16x16x32_bf16 v[10:13], v[122:125], v[222:225], v[10:13]
	v_mfma_f32_16x16x32_bf16 v[62:65], v[118:121], v[202:205], v[62:65]
	v_mfma_f32_16x16x32_bf16 v[58:61], v[126:129], v[202:205], v[58:61]
	v_mfma_f32_16x16x32_bf16 v[46:49], v[118:121], v[210:213], v[46:49]
	v_mfma_f32_16x16x32_bf16 v[42:45], v[126:129], v[210:213], v[42:45]
	v_mfma_f32_16x16x32_bf16 v[30:33], v[118:121], v[218:221], v[30:33]
	v_mfma_f32_16x16x32_bf16 v[26:29], v[126:129], v[218:221], v[26:29]
	v_mfma_f32_16x16x32_bf16 v[14:17], v[118:121], v[226:229], v[14:17]
	v_mfma_f32_16x16x32_bf16 v[10:13], v[126:129], v[226:229], v[10:13]
	s_setprio 0
	s_setprio 1
	v_mfma_f32_16x16x32_bf16 v[54:57], v[182:185], v[198:201], v[54:57]
	v_mfma_f32_16x16x32_bf16 v[50:53], v[190:193], v[198:201], v[50:53]
	v_mfma_f32_16x16x32_bf16 v[38:41], v[182:185], v[206:209], v[38:41]
	v_mfma_f32_16x16x32_bf16 v[34:37], v[190:193], v[206:209], v[34:37]
	v_mfma_f32_16x16x32_bf16 v[22:25], v[182:185], v[214:217], v[22:25]
	v_mfma_f32_16x16x32_bf16 v[18:21], v[190:193], v[214:217], v[18:21]
	v_mfma_f32_16x16x32_bf16 v[6:9], v[182:185], v[222:225], v[6:9]
	v_mfma_f32_16x16x32_bf16 v[2:5], v[190:193], v[222:225], v[2:5]
	v_mfma_f32_16x16x32_bf16 v[54:57], v[186:189], v[202:205], v[54:57]
	v_mfma_f32_16x16x32_bf16 v[50:53], v[194:197], v[202:205], v[50:53]
	v_mfma_f32_16x16x32_bf16 v[38:41], v[186:189], v[210:213], v[38:41]
	v_mfma_f32_16x16x32_bf16 v[34:37], v[194:197], v[210:213], v[34:37]
	v_mfma_f32_16x16x32_bf16 v[22:25], v[186:189], v[218:221], v[22:25]
	v_mfma_f32_16x16x32_bf16 v[18:21], v[194:197], v[218:221], v[18:21]
	v_mfma_f32_16x16x32_bf16 v[6:9], v[186:189], v[226:229], v[6:9]
	v_mfma_f32_16x16x32_bf16 v[2:5], v[194:197], v[226:229], v[2:5]
	s_setprio 0
	s_barrier
	s_add_i32 s76, s76, 2
	s_add_u32 s70, s70, 0x100
	s_addc_u32 s71, s71, 0
	s_add_u32 s20, s20, 0x100
	s_addc_u32 s21, s21, 0
	s_cmp_gt_u32 s76, 29
	s_cbranch_scc0 .LBB0_165
	s_and_b64 vcc, exec, s[56:57]
	s_cbranch_vccz .LBB0_168
	s_barrier
